# SSD chunk loop: segment between the barriers lightened - non-owner waves skip the row-sum address math (keep the trash store), next chunk's dt cumsum moved to wave 4 before the barrier
# baseline (speedup 1.0000x reference)
.LBB0_347:
	s_or_b64 exec, exec, s[0:1]
	v_mul_f32_e32 v4, 0x3fb8aa3b, v4
	v_exp_f32_e32 v63, v4
	v_cmp_gt_i32_e64 s[38:39], s35, v1
	v_add_u32_e32 v4, 0xffffff00, v1
	v_mov_b32_e32 v5, 0x1000
	v_cndmask_b32_e64 v51, v4, v1, s[38:39]
	v_mov_b32_e32 v4, 0x1200
	s_lshl_b32 s0, s36, 4
	v_cndmask_b32_e64 v4, v4, v5, s[38:39]
	s_and_b32 s0, s0, 0x180
	v_ashrrev_i32_e32 v48, 4, v51
	v_or_b32_e32 v54, s0, v4
	v_lshlrev_b32_e32 v4, 3, v51
	s_movk_i32 s0, 0x78
	s_lshl_b32 s23, s36, 6
	s_lshl_b32 s85, s37, 12
	v_and_or_b32 v4, v4, s0, v54
	s_bitset1_b32 s23, 11
	v_lshlrev_b32_e32 v50, 2, v48
	s_add_i32 s70, s85, -16
	v_and_or_b32 v20, v2, 60, s23
	v_subrev_u32_e32 v5, 48, v50
	v_lshlrev_b32_e32 v2, 1, v4
	v_cmp_lt_i32_e32 vcc, 15, v48
	v_mov_b32_e32 v52, s70
	v_lshl_add_u64 v[22:23], s[96:97], 0, v[2:3]
	v_max_i32_e32 v2, 0, v5
	v_cndmask_b32_e32 v4, v229, v52, vcc
	v_add_u32_e32 v2, v2, v4
	v_mad_i64_i32 v[4:5], s[0:1], v2, s29, v[22:23]
	v_subrev_u32_e32 v2, 47, v50
	v_cmp_lt_i32_e32 vcc, 15, v2
	v_max_i32_e32 v8, 0, v2
	v_ashrrev_i32_e32 v49, 4, v1
	v_cndmask_b32_e32 v2, v229, v52, vcc
	v_add_u32_e32 v2, v2, v8
	v_mad_i64_i32 v[8:9], s[26:27], v2, s29, v[22:23]
	v_subrev_u32_e32 v2, 46, v50
	v_cmp_lt_i32_e32 vcc, 15, v2
	v_max_i32_e32 v12, 0, v2
	v_lshlrev_b32_e32 v55, 1, v49
	v_cndmask_b32_e32 v2, v229, v52, vcc
	v_add_u32_e32 v2, v2, v12
	v_mad_i64_i32 v[12:13], s[26:27], v2, s29, v[22:23]
	v_subrev_u32_e32 v2, 45, v50
	v_cmp_lt_i32_e32 vcc, 15, v2
	v_max_i32_e32 v16, 0, v2
	v_subrev_u32_e32 v21, 48, v55
	v_cndmask_b32_e32 v2, v229, v52, vcc
	v_add_u32_e32 v2, v2, v16
	v_mad_i64_i32 v[16:17], s[26:27], v2, s29, v[22:23]
	v_lshlrev_b32_e32 v2, 1, v20
	v_cmp_lt_i32_e32 vcc, 31, v49
	v_lshl_add_u64 v[46:47], s[96:97], 0, v[2:3]
	v_max_i32_e32 v2, 0, v21
	v_cndmask_b32_e32 v20, v229, v52, vcc
	v_add_u32_e32 v2, v2, v20
	v_mad_i64_i32 v[20:21], s[26:27], v2, s29, v[46:47]
	v_subrev_u32_e32 v2, 47, v55
	v_cmp_lt_i32_e32 vcc, 15, v2
	global_load_dwordx2 v[40:41], v[20:21], off
	v_max_i32_e32 v20, 0, v2
	v_cndmask_b32_e32 v2, v229, v52, vcc
	v_and_b32_e32 v65, 63, v1
	v_add_u32_e32 v2, v2, v20
	v_mad_i64_i32 v[20:21], s[26:27], v2, s29, v[46:47]
	v_max_u32_e32 v2, 48, v65
	v_readlane_b32 s42, v252, 52
	v_lshlrev_b32_e32 v2, 7, v2
	v_readlane_b32 s43, v252, 53
	global_load_dwordx2 v[42:43], v[20:21], off
	s_mov_b32 s24, 0x3fe000
	v_lshl_add_u64 v[20:21], s[42:43], 0, v[2:3]
	v_lshl_add_u64 v[20:21], v[20:21], 0, s[72:73]
	v_add_co_u32_e32 v20, vcc, s24, v20
	v_add_u32_e32 v2, 16, v50
	s_nop 0
	v_addc_co_u32_e32 v21, vcc, 0, v21, vcc
	v_cmp_lt_i32_e32 vcc, -1, v48
	global_load_dword v20, v[20:21], off offset:2048
	v_max_i32_e32 v2, 0, v2
	v_cndmask_b32_e32 v21, v229, v52, vcc
	v_add_u32_e32 v2, v2, v21
	v_mad_i64_i32 v[24:25], s[26:27], v2, s29, v[22:23]
	v_add_u32_e32 v2, 17, v50
	v_cmp_lt_i32_e32 vcc, 15, v2
	v_max_i32_e32 v21, 0, v2
	global_load_dwordx4 v[24:27], v[24:25], off
	v_cndmask_b32_e32 v2, v229, v52, vcc
	v_add_u32_e32 v2, v2, v21
	v_mad_i64_i32 v[28:29], s[26:27], v2, s29, v[22:23]
	v_add_u32_e32 v2, 18, v50
	v_cmp_lt_i32_e32 vcc, 15, v2
	v_max_i32_e32 v21, 0, v2
	s_ashr_i32 s21, s25, 8
	v_cndmask_b32_e32 v2, v229, v52, vcc
	v_add_u32_e32 v2, v2, v21
	v_mad_i64_i32 v[32:33], s[26:27], v2, s29, v[22:23]
	v_add_u32_e32 v2, 19, v50
	v_cmp_lt_i32_e32 vcc, 15, v2
	v_max_i32_e32 v21, 0, v2
	global_load_dwordx4 v[28:31], v[28:29], off
	v_cndmask_b32_e32 v2, v229, v52, vcc
	v_add_u32_e32 v2, v2, v21
	v_mad_i64_i32 v[22:23], s[26:27], v2, s29, v[22:23]
	v_add_u32_e32 v2, 16, v55
	v_cmp_lt_i32_e32 vcc, -1, v49
	v_max_i32_e32 v2, 0, v2
	global_load_dwordx4 v[36:39], v[22:23], off
	v_cndmask_b32_e32 v21, v229, v52, vcc
	v_add_u32_e32 v2, v2, v21
	v_mad_i64_i32 v[22:23], s[26:27], v2, s29, v[46:47]
	v_add_u32_e32 v2, 17, v55
	v_cmp_lt_i32_e32 vcc, 15, v2
	v_max_i32_e32 v21, 0, v2
	global_load_dwordx2 v[44:45], v[22:23], off
	v_cndmask_b32_e32 v2, v229, v52, vcc
	v_add_u32_e32 v2, v2, v21
	v_mad_i64_i32 v[22:23], s[26:27], v2, s29, v[46:47]
	v_or_b32_e32 v56, s85, v65
	s_lshr_b32 s22, s25, 6
	s_bfe_u32 s20, s25, 0x20006
	v_ashrrev_i32_e32 v57, 31, v56
	s_lshl_b32 s24, s21, 5
	s_sub_i32 s37, s85, 64
	s_lshl_b32 s26, s36, 7
	global_load_dwordx4 v[32:35], v[32:33], off
	s_add_u32 s36, s96, s26
	global_load_dwordx2 v[46:47], v[22:23], off
	v_lshlrev_b64 v[22:23], 7, v[56:57]
	v_and_b32_e32 v94, 15, v1
	v_lshl_add_u64 v[22:23], s[42:43], 0, v[22:23]
	s_addc_u32 s42, s97, 0
	s_lshl_b32 s27, s20, 4
	s_lshl_b32 s26, s20, 5
	v_or_b32_e32 v86, s24, v94
	s_add_u32 s74, s36, s26
	v_lshrrev_b32_e32 v2, 1, v1
	v_lshl_add_u64 v[22:23], v[22:23], 0, s[72:73]
	s_addc_u32 s75, s42, 0
	v_and_b32_e32 v2, 24, v2
	v_cmp_lt_i32_e32 vcc, 63, v86
	v_mov_b32_e32 v21, s37
	global_load_dword v57, v[22:23], off
	v_lshl_add_u64 v[22:23], s[74:75], 0, v[2:3]
	v_max_i32_e32 v2, 48, v86
	v_cndmask_b32_e32 v52, v230, v21, vcc
	v_or_b32_e32 v87, 16, v86
	v_add_u32_e32 v2, v52, v2
	v_cmp_lt_i32_e32 vcc, 63, v87
	v_mad_i64_i32 v[52:53], s[36:37], v2, s29, v[22:23]
	v_max_i32_e32 v2, 48, v87
	v_cndmask_b32_e32 v21, v230, v21, vcc
	v_add_u32_e32 v2, v21, v2
	v_mad_i64_i32 v[22:23], s[36:37], v2, s29, v[22:23]
	global_load_dwordx4 v[4:7], v[4:5], off
	s_cmp_lt_u32 s25, 64
	global_load_dwordx4 v[8:11], v[8:9], off
	s_cselect_b64 s[60:61], -1, 0
	s_sub_u32 s98, s25, 0x100
	s_cmp_lt_u32 s98, 64
	s_cselect_b64 s[98:99], -1, 0
	global_load_dwordx4 v[12:15], v[12:13], off
	v_cmp_lt_i32_e64 s[0:1], 11, v48
	global_load_dwordx4 v[16:19], v[16:17], off
	v_cmp_lt_i32_e64 s[40:41], 23, v49
	global_load_dwordx2 v[52:53], v[52:53], off
	s_and_b64 vcc, exec, s[60:61]
	global_load_dwordx2 v[84:85], v[22:23], off
	s_waitcnt lgkmcnt(0)
	s_barrier
	s_cbranch_vccz .LBB0_349
	v_cmp_lt_u32_e32 vcc, 47, v65
	v_mov_b32_e32 v21, v3
	s_waitcnt vmcnt(13)
	v_cndmask_b32_e32 v2, 0, v20, vcc
	v_mul_f32_e64 v20, v2, -v63
	s_nop 1
	v_mov_b32_dpp v21, v20 row_shr:1 row_mask:0xf bank_mask:0xf
	v_fma_f32 v20, v2, -v63, v21
	v_mov_b32_e32 v21, v3
	s_nop 0
	v_add_f32_dpp v20, v20, v20 row_shr:2 row_mask:0xf bank_mask:0xf bound_ctrl:1
	s_nop 1
	v_add_f32_dpp v20, v20, v20 row_shr:4 row_mask:0xf bank_mask:0xf bound_ctrl:1
	s_nop 1
	v_add_f32_dpp v20, v20, v20 row_shr:8 row_mask:0xf bank_mask:0xf bound_ctrl:1
	s_nop 1
	v_mov_b32_dpp v21, v20 row_bcast:15 row_mask:0xa bank_mask:0xf
	v_add_f32_e32 v20, v20, v21
	v_mov_b32_e32 v21, v3
	s_nop 1
	v_mov_b32_dpp v21, v20 row_bcast:31 row_mask:0xc bank_mask:0xf
	v_add_f32_e32 v20, v20, v21
	v_lshl_add_u32 v21, v65, 2, 0
	v_add_u32_e32 v22, 0x1a400, v21
	ds_write_b32 v22, v2
	v_add_u32_e32 v2, 0x1a600, v21
	ds_write_b32 v2, v20

.LBB0_358:
	s_or_b64 exec, exec, s[0:1]
	s_cmp_eq_u32 s98, 0
	s_cbranch_scc1 .Lscan1_skip
	s_cmp_eq_u32 s81, 64
	s_cbranch_scc1 .Lscan1_skip
	v_mul_f32_e64 v198, v57, -v63
	v_mov_b32_e32 v199, v3
	s_nop 1
	v_mov_b32_dpp v199, v198 row_shr:1 row_mask:0xf bank_mask:0xf
	v_fma_f32 v198, v57, -v63, v199
	v_mov_b32_e32 v199, v3
	s_nop 0
	v_add_f32_dpp v198, v198, v198 row_shr:2 row_mask:0xf bank_mask:0xf bound_ctrl:1
	s_nop 1
	v_add_f32_dpp v198, v198, v198 row_shr:4 row_mask:0xf bank_mask:0xf bound_ctrl:1
	s_nop 1
	v_add_f32_dpp v198, v198, v198 row_shr:8 row_mask:0xf bank_mask:0xf bound_ctrl:1
	s_nop 1
	v_mov_b32_dpp v199, v198 row_bcast:15 row_mask:0xa bank_mask:0xf
	v_add_f32_e32 v198, v198, v199
	v_mov_b32_e32 v199, v3
	s_nop 1
	v_mov_b32_dpp v199, v198 row_bcast:31 row_mask:0xc bank_mask:0xf
	v_add_f32_e32 v198, v198, v199
	ds_write_b32 v104, v57
	ds_write_b32 v105, v198
.Lscan1_skip:
	v_mov_b32_e32 v54, s87
	v_add_u32_e32 v55, v71, v96
	ds_read_b32 v54, v54
	s_waitcnt vmcnt(7)
	ds_write_b64 v55, v[58:59]
	v_add_u32_e32 v55, v71, v97
	s_waitcnt vmcnt(6)
	ds_write_b64 v55, v[60:61]
	ds_read_b64 v[88:89], v99
	ds_read_b64 v[160:161], v98
	v_lshlrev_b32_e32 v157, 16, v60
	v_lshlrev_b32_e32 v156, 16, v58
	s_mul_hi_i32 s1, s21, 0x3400
	s_waitcnt lgkmcnt(1)
	v_sub_f32_e32 v55, v54, v88
	v_mul_f32_e32 v55, 0x3fb8aa3b, v55
	v_exp_f32_e32 v88, v55
	v_sub_f32_e32 v55, v54, v89
	v_mul_f32_e32 v55, 0x3fb8aa3b, v55
	v_exp_f32_e32 v89, v55
	s_waitcnt lgkmcnt(0)
	v_pk_mul_f32 v[162:163], v[160:161], v[156:157]
	s_mulk_i32 s21, 0x3400
	v_cvt_pk_bf16_f32 v55, v162, v163
	v_pk_mul_f32 v[88:89], v[160:161], v[88:89]
	s_add_u32 s0, s96, s21
	v_pk_mul_f32 v[156:157], v[88:89], v[156:157]
	s_addc_u32 s1, s97, s1
	v_cvt_pk_bf16_f32 v153, v156, v157
	v_and_b32_e32 v157, 0xffff0000, v60
	v_and_b32_e32 v156, 0xffff0000, v58
	v_pk_mul_f32 v[162:163], v[160:161], v[156:157]
	v_pk_mul_f32 v[156:157], v[88:89], v[156:157]
	v_cvt_pk_bf16_f32 v58, v162, v163
	ds_write2_b32 v126, v55, v58 offset1:36
	v_cvt_pk_bf16_f32 v55, v156, v157
	v_lshlrev_b32_e32 v157, 16, v61
	v_lshlrev_b32_e32 v156, 16, v59
	v_and_b32_e32 v61, 0xffff0000, v61
	v_and_b32_e32 v60, 0xffff0000, v59
	v_pk_mul_f32 v[162:163], v[160:161], v[156:157]
	v_pk_mul_f32 v[58:59], v[160:161], v[60:61]
	ds_write2_b32 v137, v153, v55 offset1:36
	v_cvt_pk_bf16_f32 v55, v162, v163
	v_cvt_pk_bf16_f32 v58, v58, v59
	v_lshlrev_b32_e32 v2, 1, v62
	v_pk_mul_f32 v[156:157], v[88:89], v[156:157]
	ds_write2_b32 v126, v55, v58 offset0:72 offset1:108
	v_pk_mul_f32 v[58:59], v[88:89], v[60:61]
	v_lshlrev_b32_e32 v88, 1, v64
	v_mov_b32_e32 v89, v3
	v_lshl_add_u64 v[20:21], s[0:1], 0, v[2:3]
	v_lshl_add_u64 v[60:61], s[0:1], 0, v[88:89]
	v_lshl_add_u64 v[4:5], v[72:73], 1, v[20:21]
	v_lshl_add_u64 v[8:9], v[74:75], 1, v[20:21]
	v_lshl_add_u64 v[12:13], v[76:77], 1, v[20:21]
	v_lshl_add_u64 v[20:21], v[78:79], 1, v[20:21]
	v_cvt_pk_bf16_f32 v55, v58, v59
	v_lshl_add_u64 v[58:59], v[80:81], 1, v[60:61]
	v_lshl_add_u64 v[60:61], v[82:83], 1, v[60:61]
	global_load_dwordx4 v[4:7], v[4:5], off
	s_cmp_lg_u32 s36, 0
	global_load_dwordx4 v[8:11], v[8:9], off
	v_cvt_pk_bf16_f32 v153, v156, v157
	global_load_dwordx4 v[12:15], v[12:13], off
	s_cselect_b64 s[0:1], -1, 0
	global_load_dwordx4 v[20:23], v[20:21], off
	s_max_u32 s21, s20, 1
	global_load_dwordx2 v[58:59], v[58:59], off
	ds_write2_b32 v137, v153, v55 offset0:72 offset1:108
	global_load_dwordx2 v[60:61], v[60:61], off
	v_lshl_add_u32 v55, s21, 6, v103
	v_cmp_lt_i32_e32 vcc, -1, v55
	s_waitcnt lgkmcnt(0)
	s_barrier
	s_cmp_eq_u64 s[82:83], 0
	s_cbranch_scc1 .Lssq1_own
	v_lshlrev_b32_e32 v201, 2, v232
	global_store_dword v201, v3, s[66:67]
	s_branch .LBB0_360
.Lssq1_own:
	s_and_b64 s[22:23], s[40:41], vcc
	v_cmp_lt_u32_e32 vcc, 15, v55
	s_and_b64 s[0:1], s[0:1], s[22:23]
	s_or_b64 s[22:23], s[64:65], vcc
	ds_read2st64_b32 v[156:157], v101 offset1:1
	ds_read2st64_b32 v[160:161], v101 offset0:2 offset1:3
	s_and_b64 vcc, s[0:1], s[22:23]
	v_cmp_lt_i32_e64 s[0:1], 15, v55
	v_mov_b32_e32 v89, s70
	s_cmp_eq_u32 s81, 64
	v_cndmask_b32_e64 v89, v229, v89, s[0:1]
	v_add_u32_e32 v162, v89, v55
	v_ashrrev_i32_e32 v163, 31, v162
	v_lshlrev_b64 v[162:163], 5, v[162:163]
	s_waitcnt lgkmcnt(1)
	v_mov_b32_e32 v164, v156
	s_waitcnt lgkmcnt(0)
	v_mov_b32_e32 v165, v160
	v_mov_b32_e32 v160, v157
	s_cselect_b64 s[0:1], -1, 0
	v_cndmask_b32_e32 v163, 0, v163, vcc
	v_cndmask_b32_e32 v162, v232, v162, vcc
	v_pk_add_f32 v[156:157], v[164:165], v[160:161]
	s_or_b64 s[0:1], s[82:83], s[0:1]
	v_add_f32_e32 v55, v156, v157
	v_lshl_add_u64 v[156:157], v[162:163], 2, s[66:67]
	s_and_b64 vcc, exec, s[0:1]
	global_store_dword v[156:157], v55, off
	s_cbranch_vccnz .LBB0_360

.LBB0_371:
	s_or_b64 exec, exec, s[0:1]
	s_cmp_eq_u32 s98, 0
	s_cbranch_scc1 .Lscan2_skip
	s_waitcnt vmcnt(11)
	v_mul_f32_e64 v198, v152, -v63
	v_mov_b32_e32 v199, v3
	s_nop 1
	v_mov_b32_dpp v199, v198 row_shr:1 row_mask:0xf bank_mask:0xf
	v_fma_f32 v198, v152, -v63, v199
	v_mov_b32_e32 v199, v3
	s_nop 0
	v_add_f32_dpp v198, v198, v198 row_shr:2 row_mask:0xf bank_mask:0xf bound_ctrl:1
	s_nop 1
	v_add_f32_dpp v198, v198, v198 row_shr:4 row_mask:0xf bank_mask:0xf bound_ctrl:1
	s_nop 1
	v_add_f32_dpp v198, v198, v198 row_shr:8 row_mask:0xf bank_mask:0xf bound_ctrl:1
	s_nop 1
	v_mov_b32_dpp v199, v198 row_bcast:15 row_mask:0xa bank_mask:0xf
	v_add_f32_e32 v198, v198, v199
	v_mov_b32_e32 v199, v3
	s_nop 1
	v_mov_b32_dpp v199, v198 row_bcast:31 row_mask:0xc bank_mask:0xf
	v_add_f32_e32 v198, v198, v199
	ds_write_b32 v118, v152
	ds_write_b32 v119, v198
.Lscan2_skip:
	s_mul_hi_i32 s1, s20, 0x3400
	s_mulk_i32 s20, 0x3400
	s_add_u32 s0, s96, s20
	s_addc_u32 s1, s97, s1
	v_readlane_b32 s2, v254, 36
	v_lshl_add_u64 v[32:33], s[0:1], 0, v[2:3]
	v_add_u32_e32 v54, v115, v96
	v_mov_b32_e32 v2, s2
	ds_read_b32 v2, v2
	ds_write_b64 v54, v[66:67]
	v_add_u32_e32 v54, v115, v97
	ds_write_b64 v54, v[68:69]
	ds_read_b64 v[54:55], v117
	ds_read_b64 v[162:163], v116
	v_lshlrev_b32_e32 v161, 16, v68
	v_lshlrev_b32_e32 v160, 16, v66
	v_lshl_add_u64 v[16:17], v[72:73], 1, v[32:33]
	s_waitcnt lgkmcnt(1)
	v_sub_f32_e32 v54, v2, v54
	v_sub_f32_e32 v55, v2, v55
	v_mul_f32_e32 v54, 0x3fb8aa3b, v54
	v_mul_f32_e32 v55, 0x3fb8aa3b, v55
	v_exp_f32_e32 v54, v54
	v_exp_f32_e32 v55, v55
	s_waitcnt lgkmcnt(0)
	v_pk_mul_f32 v[164:165], v[162:163], v[160:161]
	v_lshl_add_u64 v[24:25], v[74:75], 1, v[32:33]
	v_cvt_pk_bf16_f32 v89, v164, v165
	v_pk_mul_f32 v[54:55], v[162:163], v[54:55]
	v_lshl_add_u64 v[28:29], v[76:77], 1, v[32:33]
	v_pk_mul_f32 v[160:161], v[54:55], v[160:161]
	v_lshl_add_u64 v[32:33], v[78:79], 1, v[32:33]
	v_cvt_pk_bf16_f32 v155, v160, v161
	v_and_b32_e32 v161, 0xffff0000, v68
	v_and_b32_e32 v160, 0xffff0000, v66
	v_pk_mul_f32 v[164:165], v[162:163], v[160:161]
	v_pk_mul_f32 v[160:161], v[54:55], v[160:161]
	v_cvt_pk_bf16_f32 v66, v164, v165
	ds_write2_b32 v130, v89, v66 offset1:36
	v_cvt_pk_bf16_f32 v66, v160, v161
	v_lshlrev_b32_e32 v161, 16, v69
	v_lshlrev_b32_e32 v160, 16, v67
	v_and_b32_e32 v69, 0xffff0000, v69
	v_and_b32_e32 v68, 0xffff0000, v67
	ds_write2_b32 v137, v155, v66 offset1:36
	v_pk_mul_f32 v[164:165], v[162:163], v[160:161]
	v_pk_mul_f32 v[66:67], v[162:163], v[68:69]
	v_cvt_pk_bf16_f32 v89, v164, v165
	v_pk_mul_f32 v[160:161], v[54:55], v[160:161]
	v_cvt_pk_bf16_f32 v66, v66, v67
	v_pk_mul_f32 v[54:55], v[54:55], v[68:69]
	v_cvt_pk_bf16_f32 v155, v160, v161
	ds_write2_b32 v130, v89, v66 offset0:72 offset1:108
	v_cvt_pk_bf16_f32 v54, v54, v55
	v_mov_b32_e32 v89, v3
	ds_write2_b32 v137, v155, v54 offset0:72 offset1:108
	v_lshl_add_u64 v[54:55], s[0:1], 0, v[88:89]
	v_lshl_add_u64 v[66:67], v[80:81], 1, v[54:55]
	v_lshl_add_u64 v[54:55], v[82:83], 1, v[54:55]
	global_load_dwordx4 v[16:19], v[16:17], off
	v_add_u32_e32 v155, s36, v123
	global_load_dwordx4 v[24:27], v[24:25], off
	v_cmp_lt_i32_e32 vcc, -1, v155
	global_load_dwordx4 v[28:31], v[28:29], off
	s_and_b64 s[0:1], s[40:41], vcc
	global_load_dwordx4 v[32:35], v[32:33], off
	v_cmp_lt_u32_e32 vcc, 15, v155
	global_load_dwordx2 v[66:67], v[66:67], off
	s_or_b64 s[20:21], s[64:65], vcc
	global_load_dwordx2 v[68:69], v[54:55], off
	s_waitcnt lgkmcnt(0)
	s_barrier
	s_cmp_eq_u64 s[82:83], 0
	s_cbranch_scc1 .Lssq2_own
	v_lshlrev_b32_e32 v201, 2, v232
	global_store_dword v201, v3, s[66:67]
	s_branch .LBB0_373
.Lssq2_own:
	ds_read2st64_b32 v[54:55], v101 offset1:1
	ds_read2st64_b32 v[88:89], v101 offset0:2 offset1:3
	s_and_b64 vcc, s[0:1], s[20:21]
	v_cmp_lt_i32_e64 s[0:1], 15, v155
	v_mov_b32_e32 v158, s70
	s_waitcnt lgkmcnt(1)
	v_mov_b32_e32 v162, v54
	v_cndmask_b32_e64 v158, v229, v158, s[0:1]
	v_add_u32_e32 v160, v155, v158
	v_ashrrev_i32_e32 v161, 31, v160
	v_lshlrev_b64 v[160:161], 5, v[160:161]
	s_waitcnt lgkmcnt(0)
	v_mov_b32_e32 v163, v88
	v_mov_b32_e32 v88, v55
	v_cndmask_b32_e32 v161, 0, v161, vcc
	v_cndmask_b32_e32 v160, v232, v160, vcc
	v_pk_add_f32 v[54:55], v[162:163], v[88:89]
	s_andn2_b64 vcc, exec, s[60:61]
	v_add_f32_e32 v88, v54, v55
	v_lshl_add_u64 v[54:55], v[160:161], 2, s[66:67]
	global_store_dword v[54:55], v88, off
	s_cbranch_vccnz .LBB0_373
